# v20 + attention loops: first-half pre-write barrier removed (K written before the publish barrier, V writes deferred to just after it)
# baseline (speedup 1.0000x reference)
.LBB0_658:
	ds_read_b128 v[64:67], v204 offset:49152
	ds_read_b128 v[68:71], v204 offset:57344
	ds_read_b128 v[240:243], v209 offset:49152
	ds_read_b128 v[244:247], v209 offset:57344
	v_add_f32_e32 v160, 0, v161
	v_add_f32_e32 v160, v175, v160
	s_waitcnt lgkmcnt(3)
	v_mfma_f32_32x32x16_bf16 v[80:95], v[64:67], v[96:99], 0
	v_add_f32_e32 v160, v162, v160
	v_add_f32_e32 v160, v235, v160
	v_add_f32_e32 v160, v174, v160
	v_add_f32_e32 v160, v238, v160
	v_add_f32_e32 v160, v163, v160
	v_add_f32_e32 v160, v173, v160
	v_add_f32_e32 v160, v169, v160
	s_waitcnt lgkmcnt(2)
	v_mfma_f32_32x32x16_bf16 v[64:79], v[68:71], v[96:99], 0
	v_add_f32_e32 v160, v171, v160
	v_add_f32_e32 v160, v170, v160
	v_add_f32_e32 v160, v172, v160
	v_exp_f32_e32 v158, v158
	v_add_f32_e32 v160, v165, v160
	v_exp_f32_e32 v159, v159
	v_add_f32_e32 v160, v167, v160
	s_waitcnt lgkmcnt(1)
	v_mfma_f32_32x32x16_bf16 v[80:95], v[240:243], v[100:103], v[80:95]
	v_exp_f32_e32 v156, v156
	v_add_f32_e32 v160, v166, v160
	v_exp_f32_e32 v157, v157
	v_add_f32_e32 v160, v168, v160
	v_exp_f32_e32 v152, v152
	v_add_f32_e32 v160, v158, v160
	v_exp_f32_e32 v153, v153
	s_waitcnt lgkmcnt(0)
	v_mfma_f32_32x32x16_bf16 v[64:79], v[244:247], v[100:103], v[64:79]
	ds_read_b128 v[240:243], v226 offset:49152
	ds_read_b128 v[244:247], v226 offset:57344
	v_add_f32_e32 v160, v159, v160
	v_exp_f32_e32 v148, v148
	v_add_f32_e32 v160, v156, v160
	v_exp_f32_e32 v149, v149
	v_add_f32_e32 v160, v157, v160
	v_exp_f32_e32 v146, v146
	s_waitcnt lgkmcnt(1)
	v_mfma_f32_32x32x16_bf16 v[80:95], v[240:243], v[104:107], v[80:95]
	v_add_f32_e32 v160, v152, v160
	v_exp_f32_e32 v147, v147
	v_add_f32_e32 v160, v153, v160
	v_exp_f32_e32 v154, v154
	v_add_f32_e32 v160, v148, v160
	v_exp_f32_e32 v155, v155
	v_add_f32_e32 v160, v149, v160
	s_waitcnt lgkmcnt(0)
	v_mfma_f32_32x32x16_bf16 v[64:79], v[244:247], v[104:107], v[64:79]
	ds_read_b128 v[240:243], v225 offset:49152
	ds_read_b128 v[244:247], v225 offset:57344
	v_exp_f32_e32 v150, v150
	v_add_f32_e32 v160, v146, v160
	v_exp_f32_e32 v151, v151
	v_add_f32_e32 v160, v147, v160
	v_exp_f32_e32 v144, v144
	v_add_f32_e32 v160, v154, v160
	s_waitcnt lgkmcnt(1)
	v_mfma_f32_32x32x16_bf16 v[80:95], v[240:243], v[108:111], v[80:95]
	v_exp_f32_e32 v145, v145
	v_add_f32_e32 v160, v155, v160
	v_add_f32_e32 v160, v150, v160
	v_add_f32_e32 v160, v151, v160
	v_add_f32_e32 v160, v144, v160
	v_add_f32_e32 v232, v145, v160
	v_mov_b32_e32 v233, v232
	s_waitcnt lgkmcnt(0)
	v_mfma_f32_32x32x16_bf16 v[64:79], v[244:247], v[108:111], v[64:79]
	ds_read_b128 v[240:243], v227 offset:49152
	ds_read_b128 v[244:247], v227 offset:57344
	v_permlane32_swap_b32_e32 v232, v233
	s_waitcnt lgkmcnt(1)
	v_mfma_f32_32x32x16_bf16 v[80:95], v[240:243], v[112:115], v[80:95]
	s_waitcnt lgkmcnt(0)
	v_mfma_f32_32x32x16_bf16 v[64:79], v[244:247], v[112:115], v[64:79]
	ds_read_b128 v[240:243], v229 offset:49152
	ds_read_b128 v[244:247], v229 offset:57344
	s_waitcnt lgkmcnt(1)
	v_mfma_f32_32x32x16_bf16 v[80:95], v[240:243], v[116:119], v[80:95]
	s_waitcnt lgkmcnt(0)
	v_mfma_f32_32x32x16_bf16 v[64:79], v[244:247], v[116:119], v[64:79]
	ds_read_b128 v[240:243], v228 offset:49152
	ds_read_b128 v[244:247], v228 offset:57344
	s_waitcnt lgkmcnt(1)
	v_mfma_f32_32x32x16_bf16 v[80:95], v[240:243], v[120:123], v[80:95]
	s_waitcnt lgkmcnt(0)
	v_mfma_f32_32x32x16_bf16 v[64:79], v[244:247], v[120:123], v[64:79]
	ds_read_b128 v[240:243], v230 offset:49152
	ds_read_b128 v[244:247], v230 offset:57344
	v_cvt_pk_bf16_f32 v160, v161, v175
	v_cvt_pk_bf16_f32 v161, v162, v235
	v_cvt_pk_bf16_f32 v162, v174, v238
	v_cvt_pk_bf16_f32 v163, v163, v173
	v_cvt_pk_bf16_f32 v234, v169, v171
	v_cvt_pk_bf16_f32 v235, v170, v172
	s_waitcnt lgkmcnt(1)
	v_mfma_f32_32x32x16_bf16 v[80:95], v[240:243], v[124:127], v[80:95]
	v_cvt_pk_bf16_f32 v236, v165, v167
	v_permlane32_swap_b32_e32 v160, v162
	v_cvt_pk_bf16_f32 v237, v166, v168
	v_permlane32_swap_b32_e32 v234, v236
	v_cvt_pk_bf16_f32 v166, v158, v159
	s_waitcnt lgkmcnt(0)
	v_mfma_f32_32x32x16_bf16 v[64:79], v[244:247], v[124:127], v[64:79]
	v_cvt_pk_bf16_f32 v167, v156, v157
	v_cvt_pk_bf16_f32 v168, v152, v153
	v_cvt_pk_bf16_f32 v169, v148, v149
	v_cvt_pk_bf16_f32 v170, v146, v147
	v_cvt_pk_bf16_f32 v171, v154, v155
	v_cvt_pk_bf16_f32 v172, v150, v151
	v_cvt_pk_bf16_f32 v173, v144, v145
	v_permlane32_swap_b32_e32 v161, v163
	v_permlane32_swap_b32_e32 v235, v237
	v_permlane32_swap_b32_e32 v166, v168
	v_permlane32_swap_b32_e32 v167, v169
	v_permlane32_swap_b32_e32 v170, v172
	v_permlane32_swap_b32_e32 v171, v173
	v_add_co_u32_e32 v144, vcc, s33, v188
	s_nop 1
	v_addc_co_u32_e32 v145, vcc, -1, v189, vcc
	v_add_co_u32_e32 v148, vcc, s70, v188
	s_nop 1
	v_addc_co_u32_e32 v149, vcc, -1, v189, vcc
	v_add_co_u32_e32 v152, vcc, s71, v188
	global_load_dwordx4 v[144:147], v[144:145], off
	s_nop 0
	global_load_dwordx4 v[148:151], v[148:149], off
	v_addc_co_u32_e32 v153, vcc, -1, v189, vcc
	v_add_co_u32_e32 v156, vcc, s72, v188
	s_nop 1
	v_addc_co_u32_e32 v157, vcc, -1, v189, vcc
	global_load_dwordx4 v[152:155], v[152:153], off
	s_nop 0
	global_load_dwordx4 v[156:159], v[156:157], off
	ds_read_b64_tr_b16 v[238:239], v203 offset:0
	ds_read_b64_tr_b16 v[240:241], v203 offset:0x800
	ds_read_b64_tr_b16 v[242:243], v203 offset:0x1000
	ds_read_b64_tr_b16 v[244:245], v203 offset:0x1800
	ds_read_b64_tr_b16 v[246:247], v203 offset:0x2000
	ds_read_b64_tr_b16 v[248:249], v203 offset:0x2800
	ds_read_b64_tr_b16 v[180:181], v203 offset:0x3000
	ds_read_b64_tr_b16 v[182:183], v203 offset:0x3800
	s_nop 0
	s_waitcnt lgkmcnt(6)
	v_mfma_f32_32x32x16_bf16 v[0:15], v[160:163], v[238:241], v[0:15]
	s_waitcnt lgkmcnt(4)
	v_mfma_f32_32x32x16_bf16 v[0:15], v[234:237], v[242:245], v[0:15]
	s_waitcnt lgkmcnt(2)
	v_mfma_f32_32x32x16_bf16 v[0:15], v[166:169], v[246:249], v[0:15]
	s_waitcnt lgkmcnt(0)
	v_mfma_f32_32x32x16_bf16 v[0:15], v[170:173], v[180:183], v[0:15]
	ds_read_b64_tr_b16 v[180:181], v203 offset:0x200
	ds_read_b64_tr_b16 v[182:183], v203 offset:0xa00
	ds_read_b64_tr_b16 v[238:239], v203 offset:0x1200
	ds_read_b64_tr_b16 v[240:241], v203 offset:0x1a00
	ds_read_b64_tr_b16 v[242:243], v203 offset:0x2200
	ds_read_b64_tr_b16 v[244:245], v203 offset:0x2a00
	ds_read_b64_tr_b16 v[246:247], v203 offset:0x3200
	ds_read_b64_tr_b16 v[248:249], v203 offset:0x3a00
	s_nop 0
	s_waitcnt lgkmcnt(6)
	v_mfma_f32_32x32x16_bf16 v[48:63], v[160:163], v[180:183], v[48:63]
	ds_read_b64_tr_b16 v[180:181], v203 offset:0x400
	ds_read_b64_tr_b16 v[182:183], v203 offset:0xc00
	s_waitcnt lgkmcnt(6)
	v_mfma_f32_32x32x16_bf16 v[48:63], v[234:237], v[238:241], v[48:63]
	ds_read_b64_tr_b16 v[238:239], v203 offset:0x1400
	ds_read_b64_tr_b16 v[240:241], v203 offset:0x1c00
	s_waitcnt lgkmcnt(6)
	v_mfma_f32_32x32x16_bf16 v[48:63], v[166:169], v[242:245], v[48:63]
	ds_read_b64_tr_b16 v[242:243], v203 offset:0x2400
	ds_read_b64_tr_b16 v[244:245], v203 offset:0x2c00
	s_waitcnt lgkmcnt(6)
	v_mfma_f32_32x32x16_bf16 v[48:63], v[170:173], v[246:249], v[48:63]
	ds_read_b64_tr_b16 v[246:247], v203 offset:0x3400
	ds_read_b64_tr_b16 v[248:249], v203 offset:0x3c00
	s_waitcnt lgkmcnt(6)
	v_mfma_f32_32x32x16_bf16 v[32:47], v[160:163], v[180:183], v[32:47]
	ds_read_b64_tr_b16 v[180:181], v203 offset:0x600
	ds_read_b64_tr_b16 v[182:183], v203 offset:0xe00
	s_waitcnt lgkmcnt(6)
	v_mfma_f32_32x32x16_bf16 v[32:47], v[234:237], v[238:241], v[32:47]
	ds_read_b64_tr_b16 v[238:239], v203 offset:0x1600
	ds_read_b64_tr_b16 v[240:241], v203 offset:0x1e00
	s_waitcnt lgkmcnt(6)
	v_mfma_f32_32x32x16_bf16 v[32:47], v[166:169], v[242:245], v[32:47]
	ds_read_b64_tr_b16 v[242:243], v203 offset:0x2600
	ds_read_b64_tr_b16 v[244:245], v203 offset:0x2e00
	s_waitcnt lgkmcnt(6)
	v_mfma_f32_32x32x16_bf16 v[32:47], v[170:173], v[246:249], v[32:47]
	ds_read_b64_tr_b16 v[246:247], v203 offset:0x3600
	ds_read_b64_tr_b16 v[248:249], v203 offset:0x3e00
	s_waitcnt lgkmcnt(6)
	v_mfma_f32_32x32x16_bf16 v[16:31], v[160:163], v[180:183], v[16:31]
	v_max_f32_e32 v160, v81, v81
	v_max_f32_e32 v161, v80, v80
	v_max_f32_e32 v160, v161, v160
	v_max3_f32 v160, v160, v82, v83
	v_max3_f32 v160, v160, v84, v85
	v_max3_f32 v160, v160, v86, v87
	v_max3_f32 v160, v160, v88, v89
	v_max3_f32 v160, v160, v90, v91
	v_max3_f32 v160, v160, v92, v93
	s_waitcnt lgkmcnt(4)
	v_mfma_f32_32x32x16_bf16 v[16:31], v[234:237], v[238:241], v[16:31]
	v_max3_f32 v160, v160, v94, v95
	v_max3_f32 v160, v160, v64, v65
	v_max3_f32 v160, v160, v66, v67
	v_max3_f32 v160, v160, v68, v69
	v_max3_f32 v160, v160, v70, v71
	v_max3_f32 v160, v160, v72, v73
	v_max3_f32 v160, v160, v74, v75
	v_max3_f32 v160, v160, v76, v77
	s_waitcnt lgkmcnt(2)
	v_mfma_f32_32x32x16_bf16 v[16:31], v[166:169], v[242:245], v[16:31]
	v_max3_f32 v160, v160, v78, v79
	v_mov_b32_e32 v161, v160
	s_nop 1
	v_permlane32_swap_b32_e32 v160, v161
	v_max_f32_e32 v161, v161, v161
	v_max_f32_e32 v160, v160, v160
	v_max_f32_e32 v160, v160, v161
	v_sub_f32_e32 v161, v160, v164
	v_cmp_ge_f32_e32 vcc, s69, v161
	v_max_f32_e32 v161, v164, v164
	v_max_f32_e32 v160, v161, v160
	s_waitcnt lgkmcnt(0)
	v_mfma_f32_32x32x16_bf16 v[16:31], v[170:173], v[246:249], v[16:31]
	v_sub_f32_e32 v161, v164, v160
	v_mul_f32_e32 v161, 0x3e0293ee, v161
	v_exp_f32_e32 v161, v161
	s_cmp_eq_u64 vcc, exec
	s_cselect_b64 s[0:1], -1, 0
	s_waitcnt vmcnt(4)
	v_cndmask_b32_e64 v234, v161, 1.0, s[0:1]
	v_cmp_gt_f32_e32 vcc, 1.0, v234
	s_waitcnt vmcnt(7)
	s_waitcnt vmcnt(6)
	s_waitcnt vmcnt(5)
	ds_write_b128 v205, v[132:135] offset:32768
	s_waitcnt vmcnt(4)
	ds_write_b128 v206, v[140:143] offset:32768
	s_cbranch_vccz .LBB0_662
	s_and_saveexec_b64 s[24:25], s[6:7]
	ds_write_b32 v200, v234 offset:128
	s_or_b64 exec, exec, s[24:25]
	s_waitcnt lgkmcnt(0)
	v_add_u32_e32 v161, v187, v178
	ds_read_b128 v[166:169], v161 offset:224
	ds_read_b128 v[170:173], v161 offset:192
	ds_read_b128 v[180:183], v161 offset:160
	ds_read_b128 v[236:239], v161 offset:128
	s_waitcnt lgkmcnt(3)
	v_pk_mul_f32 v[12:13], v[12:13], v[166:167]
	s_waitcnt lgkmcnt(2)
	v_pk_mul_f32 v[8:9], v[8:9], v[170:171]
	s_waitcnt lgkmcnt(1)
	v_pk_mul_f32 v[4:5], v[4:5], v[180:181]
	v_pk_mul_f32 v[14:15], v[14:15], v[168:169]
	v_pk_mul_f32 v[10:11], v[10:11], v[172:173]
	v_pk_mul_f32 v[6:7], v[6:7], v[182:183]
	s_waitcnt lgkmcnt(0)
	v_pk_mul_f32 v[2:3], v[2:3], v[238:239]
	v_pk_mul_f32 v[0:1], v[0:1], v[236:237]
	v_pk_mul_f32 v[60:61], v[60:61], v[166:167]
	v_pk_mul_f32 v[56:57], v[56:57], v[170:171]
	v_pk_mul_f32 v[52:53], v[52:53], v[180:181]
	v_pk_mul_f32 v[62:63], v[62:63], v[168:169]
	v_pk_mul_f32 v[58:59], v[58:59], v[172:173]
	v_pk_mul_f32 v[54:55], v[54:55], v[182:183]
	v_pk_mul_f32 v[50:51], v[50:51], v[238:239]
	v_pk_mul_f32 v[48:49], v[48:49], v[236:237]
	v_pk_mul_f32 v[44:45], v[44:45], v[166:167]
	v_pk_mul_f32 v[40:41], v[40:41], v[170:171]
	v_pk_mul_f32 v[36:37], v[36:37], v[180:181]
	v_pk_mul_f32 v[46:47], v[46:47], v[168:169]
	v_pk_mul_f32 v[42:43], v[42:43], v[172:173]
	v_pk_mul_f32 v[38:39], v[38:39], v[182:183]
	v_pk_mul_f32 v[34:35], v[34:35], v[238:239]
	v_pk_mul_f32 v[32:33], v[32:33], v[236:237]
	v_pk_mul_f32 v[28:29], v[28:29], v[166:167]
	v_pk_mul_f32 v[24:25], v[24:25], v[170:171]
	v_pk_mul_f32 v[20:21], v[20:21], v[180:181]
	v_pk_mul_f32 v[30:31], v[30:31], v[168:169]
	v_pk_mul_f32 v[26:27], v[26:27], v[172:173]
	v_pk_mul_f32 v[22:23], v[22:23], v[182:183]
	v_pk_mul_f32 v[18:19], v[18:19], v[238:239]
	v_pk_mul_f32 v[16:17], v[16:17], v[236:237]
.LBB0_662:
	v_cndmask_b32_e64 v235, v160, v164, s[0:1]
	v_mul_f32_e32 v236, 0xbe0293ee, v235
	v_fmamk_f32 v80, v80, 0x3e0293ee, v236
	v_fmamk_f32 v81, v81, 0x3e0293ee, v236
	v_fmamk_f32 v82, v82, 0x3e0293ee, v236
	v_fmamk_f32 v83, v83, 0x3e0293ee, v236
	v_fmamk_f32 v84, v84, 0x3e0293ee, v236
	v_fmamk_f32 v85, v85, 0x3e0293ee, v236
	v_fmamk_f32 v86, v86, 0x3e0293ee, v236
	v_fmamk_f32 v87, v87, 0x3e0293ee, v236
	v_fmamk_f32 v88, v88, 0x3e0293ee, v236
	v_fmamk_f32 v89, v89, 0x3e0293ee, v236
	v_fmamk_f32 v90, v90, 0x3e0293ee, v236
	v_fmamk_f32 v91, v91, 0x3e0293ee, v236
	v_fmamk_f32 v92, v92, 0x3e0293ee, v236
	v_fmamk_f32 v93, v93, 0x3e0293ee, v236
	v_fmamk_f32 v94, v94, 0x3e0293ee, v236
	v_fmamk_f32 v95, v95, 0x3e0293ee, v236
	v_exp_f32_e32 v160, v80
	v_exp_f32_e32 v175, v81
	v_exp_f32_e32 v161, v82
	v_exp_f32_e32 v174, v83
	v_exp_f32_e32 v162, v84
	v_exp_f32_e32 v173, v85
	v_exp_f32_e32 v163, v86
	v_exp_f32_e32 v172, v87
	v_exp_f32_e32 v164, v88
	v_exp_f32_e32 v171, v89
	v_exp_f32_e32 v165, v90
	v_exp_f32_e32 v170, v91
	v_exp_f32_e32 v166, v92
	v_exp_f32_e32 v169, v93
	v_exp_f32_e32 v167, v94
	v_exp_f32_e32 v168, v95
	v_fmamk_f32 v245, v64, 0x3e0293ee, v236
	v_fmamk_f32 v246, v65, 0x3e0293ee, v236
	v_fmamk_f32 v247, v66, 0x3e0293ee, v236
	v_fmamk_f32 v248, v67, 0x3e0293ee, v236
	v_fmamk_f32 v249, v68, 0x3e0293ee, v236
	v_fmamk_f32 v238, v69, 0x3e0293ee, v236
	v_fmamk_f32 v239, v70, 0x3e0293ee, v236
	v_fmamk_f32 v240, v71, 0x3e0293ee, v236
	v_fmamk_f32 v241, v72, 0x3e0293ee, v236
	v_fmamk_f32 v242, v73, 0x3e0293ee, v236
	v_fmamk_f32 v243, v74, 0x3e0293ee, v236
	v_fmamk_f32 v244, v75, 0x3e0293ee, v236
	v_fmamk_f32 v237, v76, 0x3e0293ee, v236
	v_fmamk_f32 v250, v77, 0x3e0293ee, v236
	v_fmamk_f32 v251, v78, 0x3e0293ee, v236
	v_fmac_f32_e32 v236, 0x3e0293ee, v79
	s_waitcnt lgkmcnt(0)
	s_barrier
	ds_write_b128 v207, v[128:131]
	ds_write_b128 v208, v[136:139]
	ds_read_b128 v[64:67], v204 offset:32768
	ds_read_b128 v[68:71], v204 offset:40960
	ds_read_b128 v[180:183], v209 offset:32768
	ds_read_b128 v[210:213], v209 offset:40960
	s_waitcnt lgkmcnt(3)
	v_mfma_f32_32x32x16_bf16 v[80:95], v[64:67], v[96:99], 0
	s_waitcnt lgkmcnt(2)
	v_mfma_f32_32x32x16_bf16 v[64:79], v[68:71], v[96:99], 0
	s_waitcnt lgkmcnt(1)
	v_mfma_f32_32x32x16_bf16 v[80:95], v[180:183], v[100:103], v[80:95]
	s_waitcnt lgkmcnt(0)
	v_mfma_f32_32x32x16_bf16 v[64:79], v[210:213], v[100:103], v[64:79]
	ds_read_b128 v[180:183], v226 offset:32768
	ds_read_b128 v[210:213], v226 offset:40960
	s_waitcnt lgkmcnt(1)
	v_mfma_f32_32x32x16_bf16 v[80:95], v[180:183], v[104:107], v[80:95]
	s_waitcnt lgkmcnt(0)
	v_mfma_f32_32x32x16_bf16 v[64:79], v[210:213], v[104:107], v[64:79]
	ds_read_b128 v[180:183], v225 offset:32768
	ds_read_b128 v[210:213], v225 offset:40960
	s_waitcnt lgkmcnt(1)
	v_mfma_f32_32x32x16_bf16 v[80:95], v[180:183], v[108:111], v[80:95]
	s_waitcnt lgkmcnt(0)
	v_mfma_f32_32x32x16_bf16 v[64:79], v[210:213], v[108:111], v[64:79]
	ds_read_b128 v[180:183], v227 offset:32768
	ds_read_b128 v[210:213], v227 offset:40960
	s_waitcnt lgkmcnt(1)
	v_mfma_f32_32x32x16_bf16 v[80:95], v[180:183], v[112:115], v[80:95]
	s_waitcnt lgkmcnt(0)
	v_mfma_f32_32x32x16_bf16 v[64:79], v[210:213], v[112:115], v[64:79]
	ds_read_b128 v[180:183], v229 offset:32768
	ds_read_b128 v[210:213], v229 offset:40960
	s_waitcnt lgkmcnt(1)
	v_mfma_f32_32x32x16_bf16 v[80:95], v[180:183], v[116:119], v[80:95]
	s_waitcnt lgkmcnt(0)
	v_mfma_f32_32x32x16_bf16 v[64:79], v[210:213], v[116:119], v[64:79]
	ds_read_b128 v[180:183], v228 offset:32768
	ds_read_b128 v[210:213], v228 offset:40960
	s_waitcnt lgkmcnt(1)
	v_mfma_f32_32x32x16_bf16 v[80:95], v[180:183], v[120:123], v[80:95]
	s_waitcnt lgkmcnt(0)
	v_mfma_f32_32x32x16_bf16 v[64:79], v[210:213], v[120:123], v[64:79]
	ds_read_b128 v[180:183], v230 offset:32768
	ds_read_b128 v[210:213], v230 offset:40960
	s_waitcnt lgkmcnt(1)
	v_mfma_f32_32x32x16_bf16 v[80:95], v[180:183], v[124:127], v[80:95]
	v_exp_f32_e32 v180, v245
	v_exp_f32_e32 v245, v236
	v_add_f32_e32 v236, 0, v160
	v_add_f32_e32 v236, v175, v236
	v_add_f32_e32 v236, v161, v236
	v_add_f32_e32 v236, v174, v236
	v_add_f32_e32 v236, v162, v236
	v_add_f32_e32 v236, v173, v236
	v_add_f32_e32 v236, v163, v236
	v_add_f32_e32 v236, v172, v236
	v_add_f32_e32 v236, v164, v236
	v_add_f32_e32 v236, v171, v236
	v_add_f32_e32 v236, v165, v236
	v_add_f32_e32 v236, v170, v236
	v_add_f32_e32 v236, v166, v236
	v_exp_f32_e32 v181, v246
	v_add_f32_e32 v236, v169, v236
	v_exp_f32_e32 v182, v247
	v_add_f32_e32 v236, v167, v236
	v_exp_f32_e32 v183, v248
	v_add_f32_e32 v236, v168, v236
	s_waitcnt lgkmcnt(0)
	v_mfma_f32_32x32x16_bf16 v[64:79], v[210:213], v[124:127], v[64:79]
	v_exp_f32_e32 v210, v249
	v_add_f32_e32 v236, v180, v236
	v_exp_f32_e32 v211, v238
	v_add_f32_e32 v236, v181, v236
	v_exp_f32_e32 v212, v239
	v_add_f32_e32 v236, v182, v236
	v_exp_f32_e32 v213, v240
	v_add_f32_e32 v236, v183, v236
	v_exp_f32_e32 v238, v241
	v_add_f32_e32 v236, v210, v236
	v_exp_f32_e32 v239, v242
	v_add_f32_e32 v236, v211, v236
	v_exp_f32_e32 v240, v243
	v_add_f32_e32 v236, v212, v236
	v_exp_f32_e32 v241, v244
	v_add_f32_e32 v236, v213, v236
	v_exp_f32_e32 v242, v237
	v_add_f32_e32 v236, v238, v236
	v_exp_f32_e32 v243, v250
	v_add_f32_e32 v236, v239, v236
	v_exp_f32_e32 v244, v251
	v_add_f32_e32 v236, v240, v236
	v_add_f32_e32 v236, v241, v236
	v_add_f32_e32 v236, v242, v236
	v_add_f32_e32 v236, v243, v236
	v_add_f32_e32 v236, v244, v236
	v_add_f32_e32 v236, v245, v236
	v_mov_b32_e32 v237, v236
	v_cvt_pk_bf16_f32 v160, v160, v175
	v_cvt_pk_bf16_f32 v161, v161, v174
	v_cvt_pk_bf16_f32 v162, v162, v173
	v_cvt_pk_bf16_f32 v163, v163, v172
	v_cvt_pk_bf16_f32 v164, v164, v171
	v_cvt_pk_bf16_f32 v165, v165, v170
	v_cvt_pk_bf16_f32 v166, v166, v169
	v_cvt_pk_bf16_f32 v167, v167, v168
	v_cvt_pk_bf16_f32 v168, v180, v181
	v_cvt_pk_bf16_f32 v169, v182, v183
	v_cvt_pk_bf16_f32 v170, v210, v211
	v_cvt_pk_bf16_f32 v171, v212, v213
	v_cvt_pk_bf16_f32 v172, v238, v239
	v_cvt_pk_bf16_f32 v173, v240, v241
	v_cvt_pk_bf16_f32 v174, v242, v243
	v_cvt_pk_bf16_f32 v175, v244, v245
	s_nop 1
	v_permlane32_swap_b32_e32 v236, v237
	v_permlane32_swap_b32_e32 v160, v162
	v_permlane32_swap_b32_e32 v161, v163
	v_permlane32_swap_b32_e32 v164, v166
	v_permlane32_swap_b32_e32 v165, v167
	v_permlane32_swap_b32_e32 v168, v170
	v_permlane32_swap_b32_e32 v169, v171
	v_permlane32_swap_b32_e32 v172, v174
	v_permlane32_swap_b32_e32 v173, v175
	s_cmp_ge_u32 s35, s30
	s_cselect_b64 s[24:25], -1, 0
	s_and_b64 vcc, exec, s[24:25]
	s_cbranch_vccnz .Latt_noload_gqa
	v_add_co_u32_e32 v128, vcc, 0xffff4000, v188
	s_nop 1
	v_addc_co_u32_e32 v129, vcc, -1, v189, vcc
	v_add_co_u32_e32 v132, vcc, 0xfe6f4000, v188
	s_nop 1
	v_addc_co_u32_e32 v133, vcc, -1, v189, vcc
	v_add_co_u32_e32 v140, vcc, 0xfe700000, v188
	global_load_dwordx4 v[128:131], v[128:129], off
	s_nop 0
	global_load_dwordx4 v[132:135], v[132:133], off
	v_addc_co_u32_e32 v141, vcc, -1, v189, vcc
	global_load_dwordx4 v[136:139], v[188:189], off
	s_nop 0
	global_load_dwordx4 v[140:143], v[140:141], off

.LBB0_683:
	ds_read_b128 v[64:67], v170 offset:49152
	ds_read_b128 v[68:71], v170 offset:57344
	v_add_f32_e32 v144, 0, v145
	v_add_f32_e32 v144, v158, v144
	v_add_f32_e32 v144, v146, v144
	s_waitcnt lgkmcnt(1)
	v_mfma_f32_32x32x16_bf16 v[80:95], v[64:67], v[100:103], 0
	v_add_f32_e32 v144, v159, v144
	v_add_f32_e32 v144, v147, v144
	ds_read_b128 v[204:207], v186 offset:49152
	ds_read_b128 v[226:229], v186 offset:57344
	v_add_f32_e32 v144, v200, v144
	v_add_f32_e32 v144, v157, v144
	v_add_f32_e32 v144, v203, v144
	v_add_f32_e32 v144, v149, v144
	s_waitcnt lgkmcnt(2)
	v_mfma_f32_32x32x16_bf16 v[64:79], v[68:71], v[100:103], 0
	v_add_f32_e32 v144, v153, v144
	v_add_f32_e32 v144, v150, v144
	v_add_f32_e32 v144, v154, v144
	v_exp_f32_e32 v142, v142
	v_add_f32_e32 v144, v151, v144
	v_exp_f32_e32 v143, v143
	v_add_f32_e32 v144, v155, v144
	s_waitcnt lgkmcnt(1)
	v_mfma_f32_32x32x16_bf16 v[80:95], v[204:207], v[108:111], v[80:95]
	v_exp_f32_e32 v140, v140
	v_add_f32_e32 v144, v152, v144
	v_exp_f32_e32 v141, v141
	v_add_f32_e32 v144, v156, v144
	v_exp_f32_e32 v136, v136
	v_add_f32_e32 v144, v142, v144
	v_exp_f32_e32 v137, v137
	s_waitcnt lgkmcnt(0)
	v_mfma_f32_32x32x16_bf16 v[64:79], v[226:229], v[108:111], v[64:79]
	ds_read_b128 v[204:207], v175 offset:49152
	ds_read_b128 v[226:229], v175 offset:57344
	v_add_f32_e32 v144, v143, v144
	v_exp_f32_e32 v132, v132
	v_add_f32_e32 v144, v140, v144
	v_exp_f32_e32 v133, v133
	v_add_f32_e32 v144, v141, v144
	v_exp_f32_e32 v130, v130
	s_waitcnt lgkmcnt(1)
	v_mfma_f32_32x32x16_bf16 v[80:95], v[204:207], v[96:99], v[80:95]
	v_add_f32_e32 v144, v136, v144
	v_exp_f32_e32 v131, v131
	v_add_f32_e32 v144, v137, v144
	v_exp_f32_e32 v138, v138
	v_add_f32_e32 v144, v132, v144
	v_exp_f32_e32 v139, v139
	v_add_f32_e32 v144, v133, v144
	s_waitcnt lgkmcnt(0)
	v_mfma_f32_32x32x16_bf16 v[64:79], v[226:229], v[96:99], v[64:79]
	ds_read_b128 v[204:207], v187 offset:49152
	ds_read_b128 v[226:229], v187 offset:57344
	v_exp_f32_e32 v134, v134
	v_add_f32_e32 v144, v130, v144
	v_exp_f32_e32 v135, v135
	v_add_f32_e32 v144, v131, v144
	v_exp_f32_e32 v128, v128
	v_add_f32_e32 v144, v138, v144
	s_waitcnt lgkmcnt(1)
	v_mfma_f32_32x32x16_bf16 v[80:95], v[204:207], v[104:107], v[80:95]
	v_exp_f32_e32 v129, v129
	v_add_f32_e32 v144, v139, v144
	v_add_f32_e32 v144, v134, v144
	v_add_f32_e32 v144, v135, v144
	v_add_f32_e32 v144, v128, v144
	v_add_f32_e32 v189, v129, v144
	v_mov_b32_e32 v198, v189
	s_waitcnt lgkmcnt(0)
	v_mfma_f32_32x32x16_bf16 v[64:79], v[226:229], v[104:107], v[64:79]
	v_cvt_pk_bf16_f32 v144, v145, v158
	v_cvt_pk_bf16_f32 v145, v146, v159
	v_cvt_pk_bf16_f32 v146, v147, v200
	v_permlane32_swap_b32_e32 v189, v198
	v_cvt_pk_bf16_f32 v147, v157, v203
	v_permlane32_swap_b32_e32 v144, v146
	v_cvt_pk_bf16_f32 v200, v149, v153
	v_cvt_pk_bf16_f32 v201, v150, v154
	v_cvt_pk_bf16_f32 v202, v151, v155
	v_cvt_pk_bf16_f32 v203, v152, v156
	v_cvt_pk_bf16_f32 v150, v142, v143
	v_cvt_pk_bf16_f32 v151, v140, v141
	v_cvt_pk_bf16_f32 v152, v136, v137
	v_cvt_pk_bf16_f32 v153, v132, v133
	v_cvt_pk_bf16_f32 v154, v130, v131
	v_cvt_pk_bf16_f32 v155, v138, v139
	v_cvt_pk_bf16_f32 v156, v134, v135
	v_cvt_pk_bf16_f32 v157, v128, v129
	v_permlane32_swap_b32_e32 v145, v147
	v_permlane32_swap_b32_e32 v200, v202
	v_permlane32_swap_b32_e32 v201, v203
	v_permlane32_swap_b32_e32 v150, v152
	v_permlane32_swap_b32_e32 v151, v153
	v_permlane32_swap_b32_e32 v154, v156
	v_permlane32_swap_b32_e32 v155, v157
	v_add_co_u32_e32 v128, vcc, s33, v162
	s_nop 1
	v_addc_co_u32_e32 v129, vcc, -1, v163, vcc
	v_add_co_u32_e32 v132, vcc, s70, v162
	s_nop 1
	v_addc_co_u32_e32 v133, vcc, -1, v163, vcc
	v_add_co_u32_e32 v136, vcc, s71, v162
	global_load_dwordx4 v[128:131], v[128:129], off
	s_nop 0
	global_load_dwordx4 v[132:135], v[132:133], off
	v_addc_co_u32_e32 v137, vcc, -1, v163, vcc
	v_add_co_u32_e32 v140, vcc, s72, v162
	s_nop 1
	v_addc_co_u32_e32 v141, vcc, -1, v163, vcc
	global_load_dwordx4 v[136:139], v[136:137], off
	s_nop 0
	global_load_dwordx4 v[140:143], v[140:141], off
	ds_read_b64_tr_b16 v[204:205], v169 offset:0
	ds_read_b64_tr_b16 v[206:207], v169 offset:0x800
	ds_read_b64_tr_b16 v[226:227], v169 offset:0x1000
	ds_read_b64_tr_b16 v[228:229], v169 offset:0x1800
	ds_read_b64_tr_b16 v[230:231], v169 offset:0x2000
	ds_read_b64_tr_b16 v[232:233], v169 offset:0x2800
	ds_read_b64_tr_b16 v[234:235], v169 offset:0x3000
	ds_read_b64_tr_b16 v[236:237], v169 offset:0x3800
	s_nop 0
	s_waitcnt lgkmcnt(6)
	v_mfma_f32_32x32x16_bf16 v[0:15], v[144:147], v[204:207], v[0:15]
	ds_read_b64_tr_b16 v[204:205], v169 offset:0x200
	ds_read_b64_tr_b16 v[206:207], v169 offset:0xa00
	s_waitcnt lgkmcnt(6)
	v_mfma_f32_32x32x16_bf16 v[0:15], v[200:203], v[226:229], v[0:15]
	ds_read_b64_tr_b16 v[226:227], v169 offset:0x1200
	ds_read_b64_tr_b16 v[228:229], v169 offset:0x1a00
	s_waitcnt lgkmcnt(6)
	v_mfma_f32_32x32x16_bf16 v[0:15], v[150:153], v[230:233], v[0:15]
	ds_read_b64_tr_b16 v[230:231], v169 offset:0x2200
	ds_read_b64_tr_b16 v[232:233], v169 offset:0x2a00
	s_waitcnt lgkmcnt(6)
	v_mfma_f32_32x32x16_bf16 v[0:15], v[154:157], v[234:237], v[0:15]
	ds_read_b64_tr_b16 v[234:235], v169 offset:0x3200
	ds_read_b64_tr_b16 v[236:237], v169 offset:0x3a00
	s_waitcnt lgkmcnt(6)
	v_mfma_f32_32x32x16_bf16 v[48:63], v[144:147], v[204:207], v[48:63]
	ds_read_b64_tr_b16 v[204:205], v169 offset:0x400
	ds_read_b64_tr_b16 v[206:207], v169 offset:0xc00
	s_waitcnt lgkmcnt(6)
	v_mfma_f32_32x32x16_bf16 v[48:63], v[200:203], v[226:229], v[48:63]
	ds_read_b64_tr_b16 v[226:227], v169 offset:0x1400
	ds_read_b64_tr_b16 v[228:229], v169 offset:0x1c00
	s_waitcnt lgkmcnt(6)
	v_mfma_f32_32x32x16_bf16 v[48:63], v[150:153], v[230:233], v[48:63]
	ds_read_b64_tr_b16 v[230:231], v169 offset:0x2400
	ds_read_b64_tr_b16 v[232:233], v169 offset:0x2c00
	s_waitcnt lgkmcnt(6)
	v_mfma_f32_32x32x16_bf16 v[48:63], v[154:157], v[234:237], v[48:63]
	ds_read_b64_tr_b16 v[234:235], v169 offset:0x3400
	ds_read_b64_tr_b16 v[236:237], v169 offset:0x3c00
	s_waitcnt lgkmcnt(6)
	v_mfma_f32_32x32x16_bf16 v[32:47], v[144:147], v[204:207], v[32:47]
	ds_read_b64_tr_b16 v[204:205], v169 offset:0x600
	ds_read_b64_tr_b16 v[206:207], v169 offset:0xe00
	s_waitcnt lgkmcnt(6)
	v_mfma_f32_32x32x16_bf16 v[32:47], v[200:203], v[226:229], v[32:47]
	ds_read_b64_tr_b16 v[226:227], v169 offset:0x1600
	ds_read_b64_tr_b16 v[228:229], v169 offset:0x1e00
	s_waitcnt lgkmcnt(6)
	v_mfma_f32_32x32x16_bf16 v[32:47], v[150:153], v[230:233], v[32:47]
	ds_read_b64_tr_b16 v[230:231], v169 offset:0x2600
	ds_read_b64_tr_b16 v[232:233], v169 offset:0x2e00
	s_waitcnt lgkmcnt(6)
	v_mfma_f32_32x32x16_bf16 v[32:47], v[154:157], v[234:237], v[32:47]
	ds_read_b64_tr_b16 v[234:235], v169 offset:0x3600
	ds_read_b64_tr_b16 v[236:237], v169 offset:0x3e00
	s_waitcnt lgkmcnt(6)
	v_mfma_f32_32x32x16_bf16 v[16:31], v[144:147], v[204:207], v[16:31]
	v_max_f32_e32 v144, v81, v81
	v_max_f32_e32 v145, v80, v80
	v_max_f32_e32 v144, v145, v144
	v_max3_f32 v144, v144, v82, v83
	v_max3_f32 v144, v144, v84, v85
	v_max3_f32 v144, v144, v86, v87
	v_max3_f32 v144, v144, v88, v89
	v_max3_f32 v144, v144, v90, v91
	v_max3_f32 v144, v144, v92, v93
	s_waitcnt lgkmcnt(4)
	v_mfma_f32_32x32x16_bf16 v[16:31], v[200:203], v[226:229], v[16:31]
	v_max3_f32 v144, v144, v94, v95
	v_max3_f32 v144, v144, v64, v65
	v_max3_f32 v144, v144, v66, v67
	v_max3_f32 v144, v144, v68, v69
	v_max3_f32 v144, v144, v70, v71
	v_max3_f32 v144, v144, v72, v73
	v_max3_f32 v144, v144, v74, v75
	v_max3_f32 v144, v144, v76, v77
	s_waitcnt lgkmcnt(2)
	v_mfma_f32_32x32x16_bf16 v[16:31], v[150:153], v[230:233], v[16:31]
	v_max3_f32 v144, v144, v78, v79
	v_mov_b32_e32 v145, v144
	s_nop 1
	v_permlane32_swap_b32_e32 v144, v145
	v_max_f32_e32 v145, v145, v145
	v_max_f32_e32 v144, v144, v144
	v_max_f32_e32 v144, v144, v145
	v_sub_f32_e32 v145, v144, v148
	v_cmp_ge_f32_e32 vcc, s49, v145
	v_max_f32_e32 v145, v148, v148
	v_max_f32_e32 v144, v145, v144
	s_waitcnt lgkmcnt(0)
	v_mfma_f32_32x32x16_bf16 v[16:31], v[154:157], v[234:237], v[16:31]
	v_sub_f32_e32 v145, v148, v144
	v_mul_f32_e32 v145, 0x3e38aa3b, v145
	v_exp_f32_e32 v145, v145
	s_cmp_eq_u64 vcc, exec
	s_cselect_b64 s[0:1], -1, 0
	s_waitcnt vmcnt(4)
	v_cndmask_b32_e64 v199, v145, 1.0, s[0:1]
	v_cmp_gt_f32_e32 vcc, 1.0, v199
	s_waitcnt vmcnt(7)
	s_waitcnt vmcnt(6)
	s_waitcnt vmcnt(5)
	ds_write_b128 v171, v[116:119] offset:32768
	s_waitcnt vmcnt(4)
	ds_write_b128 v172, v[124:127] offset:32768
	s_cbranch_vccz .LBB0_687
	s_and_saveexec_b64 s[28:29], s[6:7]
	ds_write_b32 v166, v199 offset:128
	s_or_b64 exec, exec, s[28:29]
	s_waitcnt lgkmcnt(0)
	v_add_u32_e32 v145, v161, v178
	ds_read_b128 v[150:153], v145 offset:224
	ds_read_b128 v[154:157], v145 offset:192
	ds_read_b128 v[200:203], v145 offset:160
	ds_read_b128 v[204:207], v145 offset:128
	s_waitcnt lgkmcnt(3)
	v_pk_mul_f32 v[12:13], v[12:13], v[150:151]
	s_waitcnt lgkmcnt(2)
	v_pk_mul_f32 v[8:9], v[8:9], v[154:155]
	s_waitcnt lgkmcnt(1)
	v_pk_mul_f32 v[4:5], v[4:5], v[200:201]
	v_pk_mul_f32 v[14:15], v[14:15], v[152:153]
	v_pk_mul_f32 v[10:11], v[10:11], v[156:157]
	v_pk_mul_f32 v[6:7], v[6:7], v[202:203]
	s_waitcnt lgkmcnt(0)
	v_pk_mul_f32 v[2:3], v[2:3], v[206:207]
	v_pk_mul_f32 v[0:1], v[0:1], v[204:205]
	v_pk_mul_f32 v[60:61], v[60:61], v[150:151]
	v_pk_mul_f32 v[56:57], v[56:57], v[154:155]
	v_pk_mul_f32 v[52:53], v[52:53], v[200:201]
	v_pk_mul_f32 v[62:63], v[62:63], v[152:153]
	v_pk_mul_f32 v[58:59], v[58:59], v[156:157]
	v_pk_mul_f32 v[54:55], v[54:55], v[202:203]
	v_pk_mul_f32 v[50:51], v[50:51], v[206:207]
	v_pk_mul_f32 v[48:49], v[48:49], v[204:205]
	v_pk_mul_f32 v[44:45], v[44:45], v[150:151]
	v_pk_mul_f32 v[40:41], v[40:41], v[154:155]
	v_pk_mul_f32 v[36:37], v[36:37], v[200:201]
	v_pk_mul_f32 v[46:47], v[46:47], v[152:153]
	v_pk_mul_f32 v[42:43], v[42:43], v[156:157]
	v_pk_mul_f32 v[38:39], v[38:39], v[202:203]
	v_pk_mul_f32 v[34:35], v[34:35], v[206:207]
	v_pk_mul_f32 v[32:33], v[32:33], v[204:205]
	v_pk_mul_f32 v[28:29], v[28:29], v[150:151]
	v_pk_mul_f32 v[24:25], v[24:25], v[154:155]
	v_pk_mul_f32 v[20:21], v[20:21], v[200:201]
	v_pk_mul_f32 v[30:31], v[30:31], v[152:153]
	v_pk_mul_f32 v[26:27], v[26:27], v[156:157]
	v_pk_mul_f32 v[22:23], v[22:23], v[202:203]
	v_pk_mul_f32 v[18:19], v[18:19], v[206:207]
	v_pk_mul_f32 v[16:17], v[16:17], v[204:205]
.LBB0_687:
	v_cndmask_b32_e64 v200, v144, v148, s[0:1]
	v_mul_f32_e32 v201, 0xbe38aa3b, v200
	v_fmamk_f32 v80, v80, 0x3e38aa3b, v201
	v_fmamk_f32 v81, v81, 0x3e38aa3b, v201
	v_fmamk_f32 v82, v82, 0x3e38aa3b, v201
	v_fmamk_f32 v83, v83, 0x3e38aa3b, v201
	v_fmamk_f32 v84, v84, 0x3e38aa3b, v201
	v_fmamk_f32 v85, v85, 0x3e38aa3b, v201
	v_fmamk_f32 v86, v86, 0x3e38aa3b, v201
	v_fmamk_f32 v87, v87, 0x3e38aa3b, v201
	v_fmamk_f32 v88, v88, 0x3e38aa3b, v201
	v_fmamk_f32 v89, v89, 0x3e38aa3b, v201
	v_fmamk_f32 v90, v90, 0x3e38aa3b, v201
	v_fmamk_f32 v91, v91, 0x3e38aa3b, v201
	v_fmamk_f32 v92, v92, 0x3e38aa3b, v201
	v_fmamk_f32 v93, v93, 0x3e38aa3b, v201
	v_fmamk_f32 v94, v94, 0x3e38aa3b, v201
	v_fmamk_f32 v95, v95, 0x3e38aa3b, v201
	v_exp_f32_e32 v144, v80
	v_exp_f32_e32 v159, v81
	v_exp_f32_e32 v145, v82
	v_exp_f32_e32 v158, v83
	v_exp_f32_e32 v146, v84
	v_exp_f32_e32 v157, v85
	v_exp_f32_e32 v147, v86
	v_exp_f32_e32 v156, v87
	v_exp_f32_e32 v148, v88
	v_exp_f32_e32 v155, v89
	v_exp_f32_e32 v149, v90
	v_exp_f32_e32 v154, v91
	v_exp_f32_e32 v150, v92
	v_exp_f32_e32 v153, v93
	v_exp_f32_e32 v151, v94
	v_exp_f32_e32 v152, v95
	v_fmamk_f32 v225, v64, 0x3e38aa3b, v201
	v_fmamk_f32 v226, v65, 0x3e38aa3b, v201
	v_fmamk_f32 v227, v66, 0x3e38aa3b, v201
	v_fmamk_f32 v228, v67, 0x3e38aa3b, v201
	v_fmamk_f32 v229, v68, 0x3e38aa3b, v201
	v_fmamk_f32 v203, v69, 0x3e38aa3b, v201
	v_fmamk_f32 v204, v70, 0x3e38aa3b, v201
	v_fmamk_f32 v205, v71, 0x3e38aa3b, v201
	v_fmamk_f32 v206, v72, 0x3e38aa3b, v201
	v_fmamk_f32 v207, v73, 0x3e38aa3b, v201
	v_fmamk_f32 v208, v74, 0x3e38aa3b, v201
	v_fmamk_f32 v209, v75, 0x3e38aa3b, v201
	v_fmamk_f32 v202, v76, 0x3e38aa3b, v201
	v_fmamk_f32 v230, v77, 0x3e38aa3b, v201
	v_fmamk_f32 v231, v78, 0x3e38aa3b, v201
	v_fmac_f32_e32 v201, 0x3e38aa3b, v79
	s_waitcnt lgkmcnt(0)
	s_barrier
	ds_write_b128 v173, v[112:115]
	ds_write_b128 v174, v[120:123]
	ds_read_b128 v[64:67], v170 offset:32768
	ds_read_b128 v[68:71], v170 offset:40960
	v_exp_f32_e32 v180, v225
	v_exp_f32_e32 v225, v201
	v_add_f32_e32 v201, 0, v144
	v_add_f32_e32 v201, v159, v201
	s_waitcnt lgkmcnt(1)
	v_mfma_f32_32x32x16_bf16 v[80:95], v[64:67], v[100:103], 0
	v_add_f32_e32 v201, v145, v201
	v_add_f32_e32 v201, v158, v201
	v_add_f32_e32 v201, v146, v201
	ds_read_b128 v[232:235], v186 offset:32768
	ds_read_b128 v[236:239], v186 offset:40960
	v_add_f32_e32 v201, v157, v201
	v_add_f32_e32 v201, v147, v201
	v_add_f32_e32 v201, v156, v201
	s_waitcnt lgkmcnt(2)
	v_mfma_f32_32x32x16_bf16 v[64:79], v[68:71], v[100:103], 0
	v_add_f32_e32 v201, v148, v201
	v_add_f32_e32 v201, v155, v201
	v_add_f32_e32 v201, v149, v201
	v_add_f32_e32 v201, v154, v201
	v_add_f32_e32 v201, v150, v201
	v_exp_f32_e32 v181, v226
	v_add_f32_e32 v201, v153, v201
	s_waitcnt lgkmcnt(1)
	v_mfma_f32_32x32x16_bf16 v[80:95], v[232:235], v[108:111], v[80:95]
	v_exp_f32_e32 v182, v227
	v_add_f32_e32 v201, v151, v201
	v_exp_f32_e32 v183, v228
	v_add_f32_e32 v201, v152, v201
	v_exp_f32_e32 v210, v229
	v_add_f32_e32 v201, v180, v201
	v_exp_f32_e32 v203, v203
	s_waitcnt lgkmcnt(0)
	v_mfma_f32_32x32x16_bf16 v[64:79], v[236:239], v[108:111], v[64:79]
	ds_read_b128 v[232:235], v175 offset:32768
	ds_read_b128 v[236:239], v175 offset:40960
	v_add_f32_e32 v201, v181, v201
	v_exp_f32_e32 v204, v204
	v_add_f32_e32 v201, v182, v201
	v_exp_f32_e32 v205, v205
	v_add_f32_e32 v201, v183, v201
	v_exp_f32_e32 v206, v206
	s_waitcnt lgkmcnt(1)
	v_mfma_f32_32x32x16_bf16 v[80:95], v[232:235], v[96:99], v[80:95]
	v_add_f32_e32 v201, v210, v201
	v_exp_f32_e32 v207, v207
	v_add_f32_e32 v201, v203, v201
	v_exp_f32_e32 v208, v208
	v_add_f32_e32 v201, v204, v201
	v_exp_f32_e32 v209, v209
	v_add_f32_e32 v201, v205, v201
	s_waitcnt lgkmcnt(0)
	v_mfma_f32_32x32x16_bf16 v[64:79], v[236:239], v[96:99], v[64:79]
	ds_read_b128 v[232:235], v187 offset:32768
	ds_read_b128 v[236:239], v187 offset:40960
	v_exp_f32_e32 v211, v202
	v_add_f32_e32 v201, v206, v201
	v_exp_f32_e32 v212, v230
	v_add_f32_e32 v201, v207, v201
	v_exp_f32_e32 v213, v231
	v_add_f32_e32 v201, v208, v201
	s_waitcnt lgkmcnt(1)
	v_mfma_f32_32x32x16_bf16 v[80:95], v[232:235], v[104:107], v[80:95]
	v_add_f32_e32 v201, v209, v201
	v_add_f32_e32 v201, v211, v201
	v_add_f32_e32 v201, v212, v201
	v_add_f32_e32 v201, v213, v201
	v_add_f32_e32 v201, v225, v201
	v_mov_b32_e32 v202, v201
	v_cvt_pk_bf16_f32 v144, v144, v159
	s_waitcnt lgkmcnt(0)
	v_mfma_f32_32x32x16_bf16 v[64:79], v[236:239], v[104:107], v[64:79]
	v_cvt_pk_bf16_f32 v145, v145, v158
	v_cvt_pk_bf16_f32 v146, v146, v157
	v_cvt_pk_bf16_f32 v147, v147, v156
	v_cvt_pk_bf16_f32 v148, v148, v155
	v_cvt_pk_bf16_f32 v149, v149, v154
	v_cvt_pk_bf16_f32 v150, v150, v153
	v_cvt_pk_bf16_f32 v151, v151, v152
	v_cvt_pk_bf16_f32 v152, v180, v181
	v_cvt_pk_bf16_f32 v153, v182, v183
	v_cvt_pk_bf16_f32 v154, v210, v203
	v_cvt_pk_bf16_f32 v155, v204, v205
	v_cvt_pk_bf16_f32 v156, v206, v207
	v_cvt_pk_bf16_f32 v157, v208, v209
	v_cvt_pk_bf16_f32 v158, v211, v212
	v_cvt_pk_bf16_f32 v159, v213, v225
	v_permlane32_swap_b32_e32 v201, v202
	v_permlane32_swap_b32_e32 v144, v146
	v_permlane32_swap_b32_e32 v145, v147
	v_permlane32_swap_b32_e32 v148, v150
	v_permlane32_swap_b32_e32 v149, v151
	v_permlane32_swap_b32_e32 v152, v154
	v_permlane32_swap_b32_e32 v153, v155
	v_permlane32_swap_b32_e32 v156, v158
	v_permlane32_swap_b32_e32 v157, v159
	s_cmp_ge_u32 s91, s89
	s_cselect_b64 s[28:29], -1, 0
	s_and_b64 vcc, exec, s[28:29]
	s_cbranch_vccnz .Latt_noload_dif1
	v_add_co_u32_e32 v112, vcc, 0xffff4000, v162
	s_nop 1
	v_addc_co_u32_e32 v113, vcc, -1, v163, vcc
	v_add_co_u32_e32 v116, vcc, 0xfe6f4000, v162
	s_nop 1
	v_addc_co_u32_e32 v117, vcc, -1, v163, vcc
	v_add_co_u32_e32 v124, vcc, 0xfe700000, v162
	global_load_dwordx4 v[112:115], v[112:113], off
	s_nop 0
	global_load_dwordx4 v[116:119], v[116:117], off
	v_addc_co_u32_e32 v125, vcc, -1, v163, vcc
	global_load_dwordx4 v[120:123], v[162:163], off
	s_nop 0
	global_load_dwordx4 v[124:127], v[124:125], off

.LBB0_707:
	ds_read_b128 v[64:67], v170 offset:49152
	ds_read_b128 v[68:71], v170 offset:57344
	v_add_f32_e32 v144, 0, v145
	v_add_f32_e32 v144, v158, v144
	v_add_f32_e32 v144, v146, v144
	s_waitcnt lgkmcnt(1)
	v_mfma_f32_32x32x16_bf16 v[80:95], v[64:67], v[100:103], 0
	v_add_f32_e32 v144, v159, v144
	v_add_f32_e32 v144, v147, v144
	ds_read_b128 v[204:207], v186 offset:49152
	ds_read_b128 v[226:229], v186 offset:57344
	v_add_f32_e32 v144, v200, v144
	v_add_f32_e32 v144, v157, v144
	v_add_f32_e32 v144, v203, v144
	v_add_f32_e32 v144, v149, v144
	s_waitcnt lgkmcnt(2)
	v_mfma_f32_32x32x16_bf16 v[64:79], v[68:71], v[100:103], 0
	v_add_f32_e32 v144, v153, v144
	v_add_f32_e32 v144, v150, v144
	v_add_f32_e32 v144, v154, v144
	v_exp_f32_e32 v142, v142
	v_add_f32_e32 v144, v151, v144
	v_exp_f32_e32 v143, v143
	v_add_f32_e32 v144, v155, v144
	s_waitcnt lgkmcnt(1)
	v_mfma_f32_32x32x16_bf16 v[80:95], v[204:207], v[108:111], v[80:95]
	v_exp_f32_e32 v140, v140
	v_add_f32_e32 v144, v152, v144
	v_exp_f32_e32 v141, v141
	v_add_f32_e32 v144, v156, v144
	v_exp_f32_e32 v136, v136
	v_add_f32_e32 v144, v142, v144
	v_exp_f32_e32 v137, v137
	s_waitcnt lgkmcnt(0)
	v_mfma_f32_32x32x16_bf16 v[64:79], v[226:229], v[108:111], v[64:79]
	ds_read_b128 v[204:207], v175 offset:49152
	ds_read_b128 v[226:229], v175 offset:57344
	v_add_f32_e32 v144, v143, v144
	v_exp_f32_e32 v132, v132
	v_add_f32_e32 v144, v140, v144
	v_exp_f32_e32 v133, v133
	v_add_f32_e32 v144, v141, v144
	v_exp_f32_e32 v130, v130
	s_waitcnt lgkmcnt(1)
	v_mfma_f32_32x32x16_bf16 v[80:95], v[204:207], v[96:99], v[80:95]
	v_add_f32_e32 v144, v136, v144
	v_exp_f32_e32 v131, v131
	v_add_f32_e32 v144, v137, v144
	v_exp_f32_e32 v138, v138
	v_add_f32_e32 v144, v132, v144
	v_exp_f32_e32 v139, v139
	v_add_f32_e32 v144, v133, v144
	s_waitcnt lgkmcnt(0)
	v_mfma_f32_32x32x16_bf16 v[64:79], v[226:229], v[96:99], v[64:79]
	ds_read_b128 v[204:207], v187 offset:49152
	ds_read_b128 v[226:229], v187 offset:57344
	v_exp_f32_e32 v134, v134
	v_add_f32_e32 v144, v130, v144
	v_exp_f32_e32 v135, v135
	v_add_f32_e32 v144, v131, v144
	v_exp_f32_e32 v128, v128
	v_add_f32_e32 v144, v138, v144
	s_waitcnt lgkmcnt(1)
	v_mfma_f32_32x32x16_bf16 v[80:95], v[204:207], v[104:107], v[80:95]
	v_exp_f32_e32 v129, v129
	v_add_f32_e32 v144, v139, v144
	v_add_f32_e32 v144, v134, v144
	v_add_f32_e32 v144, v135, v144
	v_add_f32_e32 v144, v128, v144
	v_add_f32_e32 v189, v129, v144
	v_mov_b32_e32 v198, v189
	s_waitcnt lgkmcnt(0)
	v_mfma_f32_32x32x16_bf16 v[64:79], v[226:229], v[104:107], v[64:79]
	v_cvt_pk_bf16_f32 v144, v145, v158
	v_cvt_pk_bf16_f32 v145, v146, v159
	v_cvt_pk_bf16_f32 v146, v147, v200
	v_permlane32_swap_b32_e32 v189, v198
	v_cvt_pk_bf16_f32 v147, v157, v203
	v_permlane32_swap_b32_e32 v144, v146
	v_cvt_pk_bf16_f32 v200, v149, v153
	v_cvt_pk_bf16_f32 v201, v150, v154
	v_cvt_pk_bf16_f32 v202, v151, v155
	v_cvt_pk_bf16_f32 v203, v152, v156
	v_cvt_pk_bf16_f32 v150, v142, v143
	v_cvt_pk_bf16_f32 v151, v140, v141
	v_cvt_pk_bf16_f32 v152, v136, v137
	v_cvt_pk_bf16_f32 v153, v132, v133
	v_cvt_pk_bf16_f32 v154, v130, v131
	v_cvt_pk_bf16_f32 v155, v138, v139
	v_cvt_pk_bf16_f32 v156, v134, v135
	v_cvt_pk_bf16_f32 v157, v128, v129
	v_permlane32_swap_b32_e32 v145, v147
	v_permlane32_swap_b32_e32 v200, v202
	v_permlane32_swap_b32_e32 v201, v203
	v_permlane32_swap_b32_e32 v150, v152
	v_permlane32_swap_b32_e32 v151, v153
	v_permlane32_swap_b32_e32 v154, v156
	v_permlane32_swap_b32_e32 v155, v157
	v_add_co_u32_e32 v128, vcc, s33, v162
	s_nop 1
	v_addc_co_u32_e32 v129, vcc, -1, v163, vcc
	v_add_co_u32_e32 v132, vcc, s70, v162
	s_nop 1
	v_addc_co_u32_e32 v133, vcc, -1, v163, vcc
	v_add_co_u32_e32 v136, vcc, s71, v162
	global_load_dwordx4 v[128:131], v[128:129], off
	s_nop 0
	global_load_dwordx4 v[132:135], v[132:133], off
	v_addc_co_u32_e32 v137, vcc, -1, v163, vcc
	v_add_co_u32_e32 v140, vcc, s72, v162
	s_nop 1
	v_addc_co_u32_e32 v141, vcc, -1, v163, vcc
	global_load_dwordx4 v[136:139], v[136:137], off
	s_nop 0
	global_load_dwordx4 v[140:143], v[140:141], off
	ds_read_b64_tr_b16 v[204:205], v169 offset:0
	ds_read_b64_tr_b16 v[206:207], v169 offset:0x800
	ds_read_b64_tr_b16 v[226:227], v169 offset:0x1000
	ds_read_b64_tr_b16 v[228:229], v169 offset:0x1800
	ds_read_b64_tr_b16 v[230:231], v169 offset:0x2000
	ds_read_b64_tr_b16 v[232:233], v169 offset:0x2800
	ds_read_b64_tr_b16 v[234:235], v169 offset:0x3000
	ds_read_b64_tr_b16 v[236:237], v169 offset:0x3800
	s_nop 0
	s_waitcnt lgkmcnt(6)
	v_mfma_f32_32x32x16_bf16 v[32:47], v[144:147], v[204:207], v[32:47]
	ds_read_b64_tr_b16 v[204:205], v169 offset:0x200
	ds_read_b64_tr_b16 v[206:207], v169 offset:0xa00
	s_waitcnt lgkmcnt(6)
	v_mfma_f32_32x32x16_bf16 v[32:47], v[200:203], v[226:229], v[32:47]
	ds_read_b64_tr_b16 v[226:227], v169 offset:0x1200
	ds_read_b64_tr_b16 v[228:229], v169 offset:0x1a00
	s_waitcnt lgkmcnt(6)
	v_mfma_f32_32x32x16_bf16 v[32:47], v[150:153], v[230:233], v[32:47]
	ds_read_b64_tr_b16 v[230:231], v169 offset:0x2200
	ds_read_b64_tr_b16 v[232:233], v169 offset:0x2a00
	s_waitcnt lgkmcnt(6)
	v_mfma_f32_32x32x16_bf16 v[32:47], v[154:157], v[234:237], v[32:47]
	ds_read_b64_tr_b16 v[234:235], v169 offset:0x3200
	ds_read_b64_tr_b16 v[236:237], v169 offset:0x3a00
	s_waitcnt lgkmcnt(6)
	v_mfma_f32_32x32x16_bf16 v[48:63], v[144:147], v[204:207], v[48:63]
	ds_read_b64_tr_b16 v[204:205], v169 offset:0x400
	ds_read_b64_tr_b16 v[206:207], v169 offset:0xc00
	s_waitcnt lgkmcnt(6)
	v_mfma_f32_32x32x16_bf16 v[48:63], v[200:203], v[226:229], v[48:63]
	ds_read_b64_tr_b16 v[226:227], v169 offset:0x1400
	ds_read_b64_tr_b16 v[228:229], v169 offset:0x1c00
	s_waitcnt lgkmcnt(6)
	v_mfma_f32_32x32x16_bf16 v[48:63], v[150:153], v[230:233], v[48:63]
	ds_read_b64_tr_b16 v[230:231], v169 offset:0x2400
	ds_read_b64_tr_b16 v[232:233], v169 offset:0x2c00
	s_waitcnt lgkmcnt(6)
	v_mfma_f32_32x32x16_bf16 v[48:63], v[154:157], v[234:237], v[48:63]
	ds_read_b64_tr_b16 v[234:235], v169 offset:0x3400
	ds_read_b64_tr_b16 v[236:237], v169 offset:0x3c00
	s_waitcnt lgkmcnt(6)
	v_mfma_f32_32x32x16_bf16 v[16:31], v[144:147], v[204:207], v[16:31]
	ds_read_b64_tr_b16 v[204:205], v169 offset:0x600
	ds_read_b64_tr_b16 v[206:207], v169 offset:0xe00
	s_waitcnt lgkmcnt(6)
	v_mfma_f32_32x32x16_bf16 v[16:31], v[200:203], v[226:229], v[16:31]
	ds_read_b64_tr_b16 v[226:227], v169 offset:0x1600
	ds_read_b64_tr_b16 v[228:229], v169 offset:0x1e00
	s_waitcnt lgkmcnt(6)
	v_mfma_f32_32x32x16_bf16 v[16:31], v[150:153], v[230:233], v[16:31]
	ds_read_b64_tr_b16 v[230:231], v169 offset:0x2600
	ds_read_b64_tr_b16 v[232:233], v169 offset:0x2e00
	s_waitcnt lgkmcnt(6)
	v_mfma_f32_32x32x16_bf16 v[16:31], v[154:157], v[234:237], v[16:31]
	ds_read_b64_tr_b16 v[234:235], v169 offset:0x3600
	ds_read_b64_tr_b16 v[236:237], v169 offset:0x3e00
	s_waitcnt lgkmcnt(6)
	v_mfma_f32_32x32x16_bf16 v[0:15], v[144:147], v[204:207], v[0:15]
	v_max_f32_e32 v144, v81, v81
	v_max_f32_e32 v145, v80, v80
	v_max_f32_e32 v144, v145, v144
	v_max3_f32 v144, v144, v82, v83
	v_max3_f32 v144, v144, v84, v85
	v_max3_f32 v144, v144, v86, v87
	v_max3_f32 v144, v144, v88, v89
	v_max3_f32 v144, v144, v90, v91
	v_max3_f32 v144, v144, v92, v93
	s_waitcnt lgkmcnt(4)
	v_mfma_f32_32x32x16_bf16 v[0:15], v[200:203], v[226:229], v[0:15]
	v_max3_f32 v144, v144, v94, v95
	v_max3_f32 v144, v144, v64, v65
	v_max3_f32 v144, v144, v66, v67
	v_max3_f32 v144, v144, v68, v69
	v_max3_f32 v144, v144, v70, v71
	v_max3_f32 v144, v144, v72, v73
	v_max3_f32 v144, v144, v74, v75
	v_max3_f32 v144, v144, v76, v77
	s_waitcnt lgkmcnt(2)
	v_mfma_f32_32x32x16_bf16 v[0:15], v[150:153], v[230:233], v[0:15]
	v_max3_f32 v144, v144, v78, v79
	v_mov_b32_e32 v145, v144
	s_nop 1
	v_permlane32_swap_b32_e32 v144, v145
	v_max_f32_e32 v145, v145, v145
	v_max_f32_e32 v144, v144, v144
	v_max_f32_e32 v144, v144, v145
	v_sub_f32_e32 v145, v144, v148
	v_cmp_ge_f32_e32 vcc, s26, v145
	v_max_f32_e32 v145, v148, v148
	v_max_f32_e32 v144, v145, v144
	s_waitcnt lgkmcnt(0)
	v_mfma_f32_32x32x16_bf16 v[0:15], v[154:157], v[234:237], v[0:15]
	v_sub_f32_e32 v145, v148, v144
	v_mul_f32_e32 v145, 0x3e38aa3b, v145
	v_exp_f32_e32 v145, v145
	s_cmp_eq_u64 vcc, exec
	s_cselect_b64 s[0:1], -1, 0
	s_waitcnt vmcnt(4)
	v_cndmask_b32_e64 v199, v145, 1.0, s[0:1]
	v_cmp_gt_f32_e32 vcc, 1.0, v199
	s_waitcnt vmcnt(7)
	s_waitcnt vmcnt(6)
	s_waitcnt vmcnt(5)
	ds_write_b128 v171, v[116:119] offset:32768
	s_waitcnt vmcnt(4)
	ds_write_b128 v172, v[124:127] offset:32768
	s_cbranch_vccz .LBB0_711
	s_and_saveexec_b64 s[20:21], s[6:7]
	ds_write_b32 v166, v199 offset:128
	s_or_b64 exec, exec, s[20:21]
	s_waitcnt lgkmcnt(0)
	v_add_u32_e32 v145, v161, v178
	ds_read_b128 v[150:153], v145 offset:224
	ds_read_b128 v[154:157], v145 offset:192
	ds_read_b128 v[200:203], v145 offset:160
	ds_read_b128 v[204:207], v145 offset:128
	s_waitcnt lgkmcnt(3)
	v_pk_mul_f32 v[44:45], v[44:45], v[150:151]
	s_waitcnt lgkmcnt(2)
	v_pk_mul_f32 v[40:41], v[40:41], v[154:155]
	s_waitcnt lgkmcnt(1)
	v_pk_mul_f32 v[36:37], v[36:37], v[200:201]
	v_pk_mul_f32 v[46:47], v[46:47], v[152:153]
	v_pk_mul_f32 v[42:43], v[42:43], v[156:157]
	v_pk_mul_f32 v[38:39], v[38:39], v[202:203]
	s_waitcnt lgkmcnt(0)
	v_pk_mul_f32 v[34:35], v[34:35], v[206:207]
	v_pk_mul_f32 v[32:33], v[32:33], v[204:205]
	v_pk_mul_f32 v[60:61], v[60:61], v[150:151]
	v_pk_mul_f32 v[56:57], v[56:57], v[154:155]
	v_pk_mul_f32 v[52:53], v[52:53], v[200:201]
	v_pk_mul_f32 v[62:63], v[62:63], v[152:153]
	v_pk_mul_f32 v[58:59], v[58:59], v[156:157]
	v_pk_mul_f32 v[54:55], v[54:55], v[202:203]
	v_pk_mul_f32 v[50:51], v[50:51], v[206:207]
	v_pk_mul_f32 v[48:49], v[48:49], v[204:205]
	v_pk_mul_f32 v[28:29], v[28:29], v[150:151]
	v_pk_mul_f32 v[24:25], v[24:25], v[154:155]
	v_pk_mul_f32 v[20:21], v[20:21], v[200:201]
	v_pk_mul_f32 v[30:31], v[30:31], v[152:153]
	v_pk_mul_f32 v[26:27], v[26:27], v[156:157]
	v_pk_mul_f32 v[22:23], v[22:23], v[202:203]
	v_pk_mul_f32 v[18:19], v[18:19], v[206:207]
	v_pk_mul_f32 v[16:17], v[16:17], v[204:205]
	v_pk_mul_f32 v[12:13], v[12:13], v[150:151]
	v_pk_mul_f32 v[8:9], v[8:9], v[154:155]
	v_pk_mul_f32 v[4:5], v[4:5], v[200:201]
	v_pk_mul_f32 v[14:15], v[14:15], v[152:153]
	v_pk_mul_f32 v[10:11], v[10:11], v[156:157]
	v_pk_mul_f32 v[6:7], v[6:7], v[202:203]
	v_pk_mul_f32 v[2:3], v[2:3], v[206:207]
	v_pk_mul_f32 v[0:1], v[0:1], v[204:205]
.LBB0_711:
	v_cndmask_b32_e64 v200, v144, v148, s[0:1]
	v_mul_f32_e32 v201, 0xbe38aa3b, v200
	v_fmamk_f32 v80, v80, 0x3e38aa3b, v201
	v_fmamk_f32 v81, v81, 0x3e38aa3b, v201
	v_fmamk_f32 v82, v82, 0x3e38aa3b, v201
	v_fmamk_f32 v83, v83, 0x3e38aa3b, v201
	v_fmamk_f32 v84, v84, 0x3e38aa3b, v201
	v_fmamk_f32 v85, v85, 0x3e38aa3b, v201
	v_fmamk_f32 v86, v86, 0x3e38aa3b, v201
	v_fmamk_f32 v87, v87, 0x3e38aa3b, v201
	v_fmamk_f32 v88, v88, 0x3e38aa3b, v201
	v_fmamk_f32 v89, v89, 0x3e38aa3b, v201
	v_fmamk_f32 v90, v90, 0x3e38aa3b, v201
	v_fmamk_f32 v91, v91, 0x3e38aa3b, v201
	v_fmamk_f32 v92, v92, 0x3e38aa3b, v201
	v_fmamk_f32 v93, v93, 0x3e38aa3b, v201
	v_fmamk_f32 v94, v94, 0x3e38aa3b, v201
	v_fmamk_f32 v95, v95, 0x3e38aa3b, v201
	v_exp_f32_e32 v144, v80
	v_exp_f32_e32 v159, v81
	v_exp_f32_e32 v145, v82
	v_exp_f32_e32 v158, v83
	v_exp_f32_e32 v146, v84
	v_exp_f32_e32 v157, v85
	v_exp_f32_e32 v147, v86
	v_exp_f32_e32 v156, v87
	v_exp_f32_e32 v148, v88
	v_exp_f32_e32 v155, v89
	v_exp_f32_e32 v149, v90
	v_exp_f32_e32 v154, v91
	v_exp_f32_e32 v150, v92
	v_exp_f32_e32 v153, v93
	v_exp_f32_e32 v151, v94
	v_exp_f32_e32 v152, v95
	v_fmamk_f32 v225, v64, 0x3e38aa3b, v201
	v_fmamk_f32 v226, v65, 0x3e38aa3b, v201
	v_fmamk_f32 v227, v66, 0x3e38aa3b, v201
	v_fmamk_f32 v228, v67, 0x3e38aa3b, v201
	v_fmamk_f32 v229, v68, 0x3e38aa3b, v201
	v_fmamk_f32 v203, v69, 0x3e38aa3b, v201
	v_fmamk_f32 v204, v70, 0x3e38aa3b, v201
	v_fmamk_f32 v205, v71, 0x3e38aa3b, v201
	v_fmamk_f32 v206, v72, 0x3e38aa3b, v201
	v_fmamk_f32 v207, v73, 0x3e38aa3b, v201
	v_fmamk_f32 v208, v74, 0x3e38aa3b, v201
	v_fmamk_f32 v209, v75, 0x3e38aa3b, v201
	v_fmamk_f32 v202, v76, 0x3e38aa3b, v201
	v_fmamk_f32 v230, v77, 0x3e38aa3b, v201
	v_fmamk_f32 v231, v78, 0x3e38aa3b, v201
	v_fmac_f32_e32 v201, 0x3e38aa3b, v79
	s_waitcnt lgkmcnt(0)
	s_barrier
	ds_write_b128 v173, v[112:115]
	ds_write_b128 v174, v[120:123]
	ds_read_b128 v[64:67], v170 offset:32768
	ds_read_b128 v[68:71], v170 offset:40960
	v_exp_f32_e32 v180, v225
	v_exp_f32_e32 v225, v201
	v_add_f32_e32 v201, 0, v144
	v_add_f32_e32 v201, v159, v201
	s_waitcnt lgkmcnt(1)
	v_mfma_f32_32x32x16_bf16 v[80:95], v[64:67], v[100:103], 0
	v_add_f32_e32 v201, v145, v201
	v_add_f32_e32 v201, v158, v201
	v_add_f32_e32 v201, v146, v201
	ds_read_b128 v[232:235], v186 offset:32768
	ds_read_b128 v[236:239], v186 offset:40960
	v_add_f32_e32 v201, v157, v201
	v_add_f32_e32 v201, v147, v201
	v_add_f32_e32 v201, v156, v201
	s_waitcnt lgkmcnt(2)
	v_mfma_f32_32x32x16_bf16 v[64:79], v[68:71], v[100:103], 0
	v_add_f32_e32 v201, v148, v201
	v_add_f32_e32 v201, v155, v201
	v_add_f32_e32 v201, v149, v201
	v_add_f32_e32 v201, v154, v201
	v_add_f32_e32 v201, v150, v201
	v_exp_f32_e32 v181, v226
	v_add_f32_e32 v201, v153, v201
	s_waitcnt lgkmcnt(1)
	v_mfma_f32_32x32x16_bf16 v[80:95], v[232:235], v[108:111], v[80:95]
	v_exp_f32_e32 v182, v227
	v_add_f32_e32 v201, v151, v201
	v_exp_f32_e32 v183, v228
	v_add_f32_e32 v201, v152, v201
	v_exp_f32_e32 v210, v229
	v_add_f32_e32 v201, v180, v201
	v_exp_f32_e32 v203, v203
	s_waitcnt lgkmcnt(0)
	v_mfma_f32_32x32x16_bf16 v[64:79], v[236:239], v[108:111], v[64:79]
	ds_read_b128 v[232:235], v175 offset:32768
	ds_read_b128 v[236:239], v175 offset:40960
	v_add_f32_e32 v201, v181, v201
	v_exp_f32_e32 v204, v204
	v_add_f32_e32 v201, v182, v201
	v_exp_f32_e32 v205, v205
	v_add_f32_e32 v201, v183, v201
	v_exp_f32_e32 v206, v206
	s_waitcnt lgkmcnt(1)
	v_mfma_f32_32x32x16_bf16 v[80:95], v[232:235], v[96:99], v[80:95]
	v_add_f32_e32 v201, v210, v201
	v_exp_f32_e32 v207, v207
	v_add_f32_e32 v201, v203, v201
	v_exp_f32_e32 v208, v208
	v_add_f32_e32 v201, v204, v201
	v_exp_f32_e32 v209, v209
	v_add_f32_e32 v201, v205, v201
	s_waitcnt lgkmcnt(0)
	v_mfma_f32_32x32x16_bf16 v[64:79], v[236:239], v[96:99], v[64:79]
	ds_read_b128 v[232:235], v187 offset:32768
	ds_read_b128 v[236:239], v187 offset:40960
	v_exp_f32_e32 v211, v202
	v_add_f32_e32 v201, v206, v201
	v_exp_f32_e32 v212, v230
	v_add_f32_e32 v201, v207, v201
	v_exp_f32_e32 v213, v231
	v_add_f32_e32 v201, v208, v201
	s_waitcnt lgkmcnt(1)
	v_mfma_f32_32x32x16_bf16 v[80:95], v[232:235], v[104:107], v[80:95]
	v_add_f32_e32 v201, v209, v201
	v_add_f32_e32 v201, v211, v201
	v_add_f32_e32 v201, v212, v201
	v_add_f32_e32 v201, v213, v201
	v_add_f32_e32 v201, v225, v201
	v_mov_b32_e32 v202, v201
	v_cvt_pk_bf16_f32 v144, v144, v159
	s_waitcnt lgkmcnt(0)
	v_mfma_f32_32x32x16_bf16 v[64:79], v[236:239], v[104:107], v[64:79]
	v_cvt_pk_bf16_f32 v145, v145, v158
	v_cvt_pk_bf16_f32 v146, v146, v157
	v_cvt_pk_bf16_f32 v147, v147, v156
	v_cvt_pk_bf16_f32 v148, v148, v155
	v_cvt_pk_bf16_f32 v149, v149, v154
	v_cvt_pk_bf16_f32 v150, v150, v153
	v_cvt_pk_bf16_f32 v151, v151, v152
	v_cvt_pk_bf16_f32 v152, v180, v181
	v_cvt_pk_bf16_f32 v153, v182, v183
	v_cvt_pk_bf16_f32 v154, v210, v203
	v_cvt_pk_bf16_f32 v155, v204, v205
	v_cvt_pk_bf16_f32 v156, v206, v207
	v_cvt_pk_bf16_f32 v157, v208, v209
	v_cvt_pk_bf16_f32 v158, v211, v212
	v_cvt_pk_bf16_f32 v159, v213, v225
	v_permlane32_swap_b32_e32 v201, v202
	v_permlane32_swap_b32_e32 v144, v146
	v_permlane32_swap_b32_e32 v145, v147
	v_permlane32_swap_b32_e32 v148, v150
	v_permlane32_swap_b32_e32 v149, v151
	v_permlane32_swap_b32_e32 v152, v154
	v_permlane32_swap_b32_e32 v153, v155
	v_permlane32_swap_b32_e32 v156, v158
	v_permlane32_swap_b32_e32 v157, v159
	s_cmp_ge_u32 s30, s89
	s_cselect_b64 s[20:21], -1, 0
	s_and_b64 vcc, exec, s[20:21]
	s_cbranch_vccnz .Latt_noload_dif2
	v_add_co_u32_e32 v112, vcc, 0xffff4000, v162
	s_nop 1
	v_addc_co_u32_e32 v113, vcc, -1, v163, vcc
	v_add_co_u32_e32 v116, vcc, 0xfe6f4000, v162
	s_nop 1
	v_addc_co_u32_e32 v117, vcc, -1, v163, vcc
	v_add_co_u32_e32 v124, vcc, 0xfe700000, v162
	global_load_dwordx4 v[112:115], v[112:113], off
	s_nop 0
	global_load_dwordx4 v[116:119], v[116:117], off
	v_addc_co_u32_e32 v125, vcc, -1, v163, vcc
	global_load_dwordx4 v[120:123], v[162:163], off
	s_nop 0
	global_load_dwordx4 v[124:127], v[124:125], off
